# diff-task epilogue: batch the 16 serialized z/subg loads up front, pair groups via permlane32_swap into 4 dwordx4 stores
# speedup vs baseline: 1.0054x; 1.0050x over previous
.LBB0_355:
	s_or_b64 exec, exec, s[10:11]
	s_and_saveexec_b64 s[4:5], s[40:41]
	s_cbranch_execz .LBB0_216
	v_and_b32_e32 v2, 64, v210
	v_xor_b32_e32 v0, 32, v210
	v_add_u32_e32 v2, 64, v2
	v_cmp_lt_i32_e32 vcc, v0, v2
	s_nop 1
	v_cndmask_b32_e32 v0, v210, v0, vcc
	v_lshlrev_b32_e32 v86, 2, v0
	ds_bpermute_b32 v0, v86, v188
	s_waitcnt lgkmcnt(0)
	v_add_f32_e32 v0, v188, v0
	v_rcp_f32_e32 v0, v0
	s_nop 0
	ds_bpermute_b32 v2, v86, v181
	s_waitcnt lgkmcnt(0)
	v_add_f32_e32 v2, v181, v2
	v_rcp_f32_e32 v4, v2
	s_nop 0
	v_mul_f32_e32 v2, v140, v4
	v_pk_mul_f32 v[4:5], v[64:65], v[2:3] op_sel_hi:[1,0]
	v_pk_mul_f32 v[8:9], v[44:45], v[2:3] op_sel_hi:[1,0]
	v_pk_fma_f32 v[82:83], v[48:49], v[0:1], v[4:5] op_sel_hi:[1,0,1] neg_lo:[0,0,1] neg_hi:[0,0,1]
	v_pk_mul_f32 v[4:5], v[66:67], v[2:3] op_sel_hi:[1,0]
	v_pk_mul_f32 v[6:7], v[82:83], v[82:83]
	v_pk_fma_f32 v[80:81], v[50:51], v[0:1], v[4:5] op_sel_hi:[1,0,1] neg_lo:[0,0,1] neg_hi:[0,0,1]
	v_pk_mul_f32 v[4:5], v[68:69], v[2:3] op_sel_hi:[1,0]
	v_pk_mul_f32 v[84:85], v[80:81], v[80:81]
	v_pk_fma_f32 v[66:67], v[52:53], v[0:1], v[4:5] op_sel_hi:[1,0,1] neg_lo:[0,0,1] neg_hi:[0,0,1]
	v_pk_mul_f32 v[4:5], v[70:71], v[2:3] op_sel_hi:[1,0]
	v_pk_fma_f32 v[10:11], v[28:29], v[0:1], v[8:9] op_sel_hi:[1,0,1] neg_lo:[0,0,1] neg_hi:[0,0,1]
	v_pk_fma_f32 v[64:65], v[54:55], v[0:1], v[4:5] op_sel_hi:[1,0,1] neg_lo:[0,0,1] neg_hi:[0,0,1]
	v_pk_mul_f32 v[4:5], v[72:73], v[2:3] op_sel_hi:[1,0]
	v_pk_mul_f32 v[68:69], v[66:67], v[66:67]
	v_pk_fma_f32 v[54:55], v[56:57], v[0:1], v[4:5] op_sel_hi:[1,0,1] neg_lo:[0,0,1] neg_hi:[0,0,1]
	v_pk_mul_f32 v[4:5], v[74:75], v[2:3] op_sel_hi:[1,0]
	v_pk_mul_f32 v[70:71], v[64:65], v[64:65]
	v_pk_fma_f32 v[52:53], v[58:59], v[0:1], v[4:5] op_sel_hi:[1,0,1] neg_lo:[0,0,1] neg_hi:[0,0,1]
	v_pk_mul_f32 v[4:5], v[76:77], v[2:3] op_sel_hi:[1,0]
	v_pk_mul_f32 v[56:57], v[54:55], v[54:55]
	v_pk_fma_f32 v[50:51], v[60:61], v[0:1], v[4:5] op_sel_hi:[1,0,1] neg_lo:[0,0,1] neg_hi:[0,0,1]
	v_pk_mul_f32 v[4:5], v[78:79], v[2:3] op_sel_hi:[1,0]
	v_pk_mul_f32 v[58:59], v[52:53], v[52:53]
	v_pk_fma_f32 v[48:49], v[62:63], v[0:1], v[4:5] op_sel_hi:[1,0,1] neg_lo:[0,0,1] neg_hi:[0,0,1]
	v_pk_mul_f32 v[4:5], v[32:33], v[2:3] op_sel_hi:[1,0]
	v_pk_mul_f32 v[60:61], v[50:51], v[50:51]
	v_pk_fma_f32 v[32:33], v[16:17], v[0:1], v[4:5] op_sel_hi:[1,0,1] neg_lo:[0,0,1] neg_hi:[0,0,1]
	v_pk_mul_f32 v[4:5], v[34:35], v[2:3] op_sel_hi:[1,0]
	v_pk_mul_f32 v[62:63], v[48:49], v[48:49]
	v_pk_fma_f32 v[18:19], v[18:19], v[0:1], v[4:5] op_sel_hi:[1,0,1] neg_lo:[0,0,1] neg_hi:[0,0,1]
	v_pk_mul_f32 v[4:5], v[36:37], v[2:3] op_sel_hi:[1,0]
	v_pk_mul_f32 v[72:73], v[32:33], v[32:33]
	v_pk_fma_f32 v[16:17], v[20:21], v[0:1], v[4:5] op_sel_hi:[1,0,1] neg_lo:[0,0,1] neg_hi:[0,0,1]
	v_pk_mul_f32 v[4:5], v[38:39], v[2:3] op_sel_hi:[1,0]
	v_pk_mul_f32 v[34:35], v[18:19], v[18:19]
	v_pk_fma_f32 v[14:15], v[22:23], v[0:1], v[4:5] op_sel_hi:[1,0,1] neg_lo:[0,0,1] neg_hi:[0,0,1]
	v_pk_mul_f32 v[4:5], v[40:41], v[2:3] op_sel_hi:[1,0]
	v_pk_mul_f32 v[20:21], v[16:17], v[16:17]
	v_pk_fma_f32 v[12:13], v[24:25], v[0:1], v[4:5] op_sel_hi:[1,0,1] neg_lo:[0,0,1] neg_hi:[0,0,1]
	v_pk_mul_f32 v[4:5], v[42:43], v[2:3] op_sel_hi:[1,0]
	v_pk_mul_f32 v[2:3], v[46:47], v[2:3] op_sel_hi:[1,0]
	v_pk_fma_f32 v[4:5], v[26:27], v[0:1], v[4:5] op_sel_hi:[1,0,1] neg_lo:[0,0,1] neg_hi:[0,0,1]
	v_pk_fma_f32 v[8:9], v[30:31], v[0:1], v[2:3] op_sel_hi:[1,0,1] neg_lo:[0,0,1] neg_hi:[0,0,1]
	v_add_f32_e32 v0, v6, v7
	v_add_f32_e32 v0, v84, v0
	v_add_f32_e32 v0, v85, v0
	v_add_f32_e32 v0, v68, v0
	v_add_f32_e32 v0, v69, v0
	v_add_f32_e32 v0, v70, v0
	v_add_f32_e32 v0, v71, v0
	v_add_f32_e32 v0, v56, v0
	v_add_f32_e32 v0, v57, v0
	v_add_f32_e32 v0, v58, v0
	v_add_f32_e32 v0, v59, v0
	v_add_f32_e32 v0, v60, v0
	v_add_f32_e32 v0, v61, v0
	v_add_f32_e32 v0, v62, v0
	v_add_f32_e32 v0, v63, v0
	v_add_f32_e32 v0, v72, v0
	v_add_f32_e32 v0, v73, v0
	v_add_f32_e32 v0, v34, v0
	v_add_f32_e32 v0, v35, v0
	v_add_f32_e32 v0, v20, v0
	v_pk_mul_f32 v[22:23], v[14:15], v[14:15]
	v_add_f32_e32 v0, v21, v0
	v_add_f32_e32 v0, v22, v0
	v_pk_mul_f32 v[24:25], v[12:13], v[12:13]
	v_add_f32_e32 v0, v23, v0
	v_add_f32_e32 v0, v24, v0
	v_pk_mul_f32 v[26:27], v[4:5], v[4:5]
	v_add_f32_e32 v0, v25, v0
	v_add_f32_e32 v0, v26, v0
	v_pk_mul_f32 v[28:29], v[10:11], v[10:11]
	v_add_f32_e32 v0, v27, v0
	v_add_f32_e32 v0, v28, v0
	v_pk_mul_f32 v[2:3], v[8:9], v[8:9]
	v_add_f32_e32 v0, v29, v0
	v_add_f32_e32 v0, v2, v0
	v_add_f32_e32 v20, v3, v0
	ds_bpermute_b32 v21, v86, v20
	s_and_b64 exec, exec, s[6:7]
	s_cbranch_execz .LBB0_216
	v_mov_b32_e32 v143, v1
	v_lshl_add_u64 v[2:3], v[144:145], 0, v[142:143]
	s_mov_b64 s[6:7], 0x1400
	v_lshl_add_u64 v[6:7], v[2:3], 0, s[6:7]
	s_mov_b64 s[6:7], 0x1000
	v_lshl_add_u64 v[2:3], v[2:3], 0, s[6:7]
	v_mad_i64_i32 v[6:7], s[6:7], v149, s96, v[6:7]
	v_mad_i64_i32 v[24:25], s[6:7], v149, s96, v[2:3]
	v_lshlrev_b32_e32 v0, 1, v147
	v_lshl_add_u64 v[2:3], v[6:7], 0, v[0:1]
	v_lshl_add_u64 v[6:7], v[24:25], 0, v[0:1]
	s_waitcnt lgkmcnt(0)
	v_add_f32_e32 v0, v20, v21
	v_fmamk_f32 v0, v0, 0x3c800000, v170
	s_mov_b32 s0, 0x800000
	v_cmp_gt_f32_e32 vcc, s0, v0
	v_mul_f32_e32 v20, 0x4b800000, v0
	v_readlane_b32 s10, v254, 22
	v_cndmask_b32_e32 v0, v0, v20, vcc
	v_rsq_f32_e32 v0, v0
	v_lshlrev_b32_e32 v22, 2, v147
	v_readlane_b32 s11, v254, 23
	v_sub_f32_e32 v23, 1.0, v141
	v_mul_f32_e32 v20, 0x45800000, v0
	v_cndmask_b32_e32 v0, v0, v20, vcc
	v_mul_f32_e32 v0, v23, v0
	v_lshlrev_b32_e32 v186, 1, v147
	v_mov_b32_e32 v187, 0
	v_lshl_add_u64 v[184:185], v[6:7], 0, v[186:187]
	global_load_dwordx2 v[108:109], v[2:3], off
	global_load_dwordx2 v[110:111], v[2:3], off offset:16
	global_load_dwordx2 v[112:113], v[2:3], off offset:32
	global_load_dwordx2 v[114:115], v[2:3], off offset:48
	global_load_dwordx2 v[116:117], v[2:3], off offset:64
	global_load_dwordx2 v[118:119], v[2:3], off offset:80
	global_load_dwordx2 v[120:121], v[2:3], off offset:96
	global_load_dwordx2 v[122:123], v[2:3], off offset:112
	global_load_dwordx4 v[124:127], v22, s[10:11]
	global_load_dwordx4 v[128:131], v22, s[10:11] offset:32
	global_load_dwordx4 v[132:135], v22, s[10:11] offset:64
	global_load_dwordx4 v[136:139], v22, s[10:11] offset:96
	global_load_dwordx4 v[140:143], v22, s[10:11] offset:128
	global_load_dwordx4 v[144:147], v22, s[10:11] offset:160
	global_load_dwordx4 v[148:151], v22, s[10:11] offset:192
	global_load_dwordx4 v[152:155], v22, s[10:11] offset:224
	v_pk_mul_f32 v[24:25], v[82:83], v[0:1] op_sel_hi:[1,0]
	v_pk_mul_f32 v[26:27], v[80:81], v[0:1] op_sel_hi:[1,0]
	s_waitcnt vmcnt(7)
	v_lshlrev_b32_e32 v156, 16, v108
	v_and_b32_e32 v157, 0xffff0000, v108
	v_lshlrev_b32_e32 v158, 16, v109
	v_and_b32_e32 v159, 0xffff0000, v109
	v_mul_f32_e32 v160, 0xbfb8aa3b, v156
	v_mul_f32_e32 v161, 0xbfb8aa3b, v157
	v_mul_f32_e32 v162, 0xbfb8aa3b, v158
	v_mul_f32_e32 v163, 0xbfb8aa3b, v159
	v_exp_f32_e32 v160, v160
	v_exp_f32_e32 v161, v161
	v_exp_f32_e32 v162, v162
	v_exp_f32_e32 v163, v163
	v_pk_mul_f32 v[24:25], v[24:25], v[124:125]
	v_pk_mul_f32 v[26:27], v[26:27], v[126:127]
	v_pk_add_f32 v[160:161], v[160:161], 1.0 op_sel_hi:[1,0]
	v_pk_add_f32 v[162:163], v[162:163], 1.0 op_sel_hi:[1,0]
	s_nop 0
	v_rcp_f32_e32 v160, v160
	v_rcp_f32_e32 v161, v161
	v_rcp_f32_e32 v162, v162
	v_rcp_f32_e32 v163, v163
	s_nop 0
	v_mul_f32_e32 v160, v156, v160
	v_mul_f32_e32 v161, v157, v161
	v_mul_f32_e32 v162, v158, v162
	v_mul_f32_e32 v163, v159, v163
	v_pk_mul_f32 v[24:25], v[24:25], v[160:161]
	v_pk_mul_f32 v[26:27], v[26:27], v[162:163]
	v_cvt_pk_bf16_f32 v164, v24, v25
	v_cvt_pk_bf16_f32 v165, v26, v27
	v_pk_mul_f32 v[24:25], v[66:67], v[0:1] op_sel_hi:[1,0]
	v_pk_mul_f32 v[26:27], v[64:65], v[0:1] op_sel_hi:[1,0]
	s_waitcnt vmcnt(6)
	v_lshlrev_b32_e32 v156, 16, v110
	v_and_b32_e32 v157, 0xffff0000, v110
	v_lshlrev_b32_e32 v158, 16, v111
	v_and_b32_e32 v159, 0xffff0000, v111
	v_mul_f32_e32 v160, 0xbfb8aa3b, v156
	v_mul_f32_e32 v161, 0xbfb8aa3b, v157
	v_mul_f32_e32 v162, 0xbfb8aa3b, v158
	v_mul_f32_e32 v163, 0xbfb8aa3b, v159
	v_exp_f32_e32 v160, v160
	v_exp_f32_e32 v161, v161
	v_exp_f32_e32 v162, v162
	v_exp_f32_e32 v163, v163
	v_pk_mul_f32 v[24:25], v[24:25], v[128:129]
	v_pk_mul_f32 v[26:27], v[26:27], v[130:131]
	v_pk_add_f32 v[160:161], v[160:161], 1.0 op_sel_hi:[1,0]
	v_pk_add_f32 v[162:163], v[162:163], 1.0 op_sel_hi:[1,0]
	s_nop 0
	v_rcp_f32_e32 v160, v160
	v_rcp_f32_e32 v161, v161
	v_rcp_f32_e32 v162, v162
	v_rcp_f32_e32 v163, v163
	s_nop 0
	v_mul_f32_e32 v160, v156, v160
	v_mul_f32_e32 v161, v157, v161
	v_mul_f32_e32 v162, v158, v162
	v_mul_f32_e32 v163, v159, v163
	v_pk_mul_f32 v[24:25], v[24:25], v[160:161]
	v_pk_mul_f32 v[26:27], v[26:27], v[162:163]
	v_cvt_pk_bf16_f32 v166, v24, v25
	v_cvt_pk_bf16_f32 v167, v26, v27
	s_nop 1
	v_permlane32_swap_b32_e32 v164, v166
	v_permlane32_swap_b32_e32 v165, v167
	global_store_dwordx4 v[184:185], v[164:167], off
	v_pk_mul_f32 v[24:25], v[54:55], v[0:1] op_sel_hi:[1,0]
	v_pk_mul_f32 v[26:27], v[52:53], v[0:1] op_sel_hi:[1,0]
	s_waitcnt vmcnt(6)
	v_lshlrev_b32_e32 v156, 16, v112
	v_and_b32_e32 v157, 0xffff0000, v112
	v_lshlrev_b32_e32 v158, 16, v113
	v_and_b32_e32 v159, 0xffff0000, v113
	v_mul_f32_e32 v160, 0xbfb8aa3b, v156
	v_mul_f32_e32 v161, 0xbfb8aa3b, v157
	v_mul_f32_e32 v162, 0xbfb8aa3b, v158
	v_mul_f32_e32 v163, 0xbfb8aa3b, v159
	v_exp_f32_e32 v160, v160
	v_exp_f32_e32 v161, v161
	v_exp_f32_e32 v162, v162
	v_exp_f32_e32 v163, v163
	v_pk_mul_f32 v[24:25], v[24:25], v[132:133]
	v_pk_mul_f32 v[26:27], v[26:27], v[134:135]
	v_pk_add_f32 v[160:161], v[160:161], 1.0 op_sel_hi:[1,0]
	v_pk_add_f32 v[162:163], v[162:163], 1.0 op_sel_hi:[1,0]
	s_nop 0
	v_rcp_f32_e32 v160, v160
	v_rcp_f32_e32 v161, v161
	v_rcp_f32_e32 v162, v162
	v_rcp_f32_e32 v163, v163
	s_nop 0
	v_mul_f32_e32 v160, v156, v160
	v_mul_f32_e32 v161, v157, v161
	v_mul_f32_e32 v162, v158, v162
	v_mul_f32_e32 v163, v159, v163
	v_pk_mul_f32 v[24:25], v[24:25], v[160:161]
	v_pk_mul_f32 v[26:27], v[26:27], v[162:163]
	v_cvt_pk_bf16_f32 v172, v24, v25
	v_cvt_pk_bf16_f32 v173, v26, v27
	v_pk_mul_f32 v[24:25], v[50:51], v[0:1] op_sel_hi:[1,0]
	v_pk_mul_f32 v[26:27], v[48:49], v[0:1] op_sel_hi:[1,0]
	s_waitcnt vmcnt(5)
	v_lshlrev_b32_e32 v156, 16, v114
	v_and_b32_e32 v157, 0xffff0000, v114
	v_lshlrev_b32_e32 v158, 16, v115
	v_and_b32_e32 v159, 0xffff0000, v115
	v_mul_f32_e32 v160, 0xbfb8aa3b, v156
	v_mul_f32_e32 v161, 0xbfb8aa3b, v157
	v_mul_f32_e32 v162, 0xbfb8aa3b, v158
	v_mul_f32_e32 v163, 0xbfb8aa3b, v159
	v_exp_f32_e32 v160, v160
	v_exp_f32_e32 v161, v161
	v_exp_f32_e32 v162, v162
	v_exp_f32_e32 v163, v163
	v_pk_mul_f32 v[24:25], v[24:25], v[136:137]
	v_pk_mul_f32 v[26:27], v[26:27], v[138:139]
	v_pk_add_f32 v[160:161], v[160:161], 1.0 op_sel_hi:[1,0]
	v_pk_add_f32 v[162:163], v[162:163], 1.0 op_sel_hi:[1,0]
	s_nop 0
	v_rcp_f32_e32 v160, v160
	v_rcp_f32_e32 v161, v161
	v_rcp_f32_e32 v162, v162
	v_rcp_f32_e32 v163, v163
	s_nop 0
	v_mul_f32_e32 v160, v156, v160
	v_mul_f32_e32 v161, v157, v161
	v_mul_f32_e32 v162, v158, v162
	v_mul_f32_e32 v163, v159, v163
	v_pk_mul_f32 v[24:25], v[24:25], v[160:161]
	v_pk_mul_f32 v[26:27], v[26:27], v[162:163]
	v_cvt_pk_bf16_f32 v174, v24, v25
	v_cvt_pk_bf16_f32 v175, v26, v27
	s_nop 1
	v_permlane32_swap_b32_e32 v172, v174
	v_permlane32_swap_b32_e32 v173, v175
	global_store_dwordx4 v[184:185], v[172:175], off offset:32
	v_pk_mul_f32 v[24:25], v[32:33], v[0:1] op_sel_hi:[1,0]
	v_pk_mul_f32 v[26:27], v[18:19], v[0:1] op_sel_hi:[1,0]
	s_waitcnt vmcnt(5)
	v_lshlrev_b32_e32 v156, 16, v116
	v_and_b32_e32 v157, 0xffff0000, v116
	v_lshlrev_b32_e32 v158, 16, v117
	v_and_b32_e32 v159, 0xffff0000, v117
	v_mul_f32_e32 v160, 0xbfb8aa3b, v156
	v_mul_f32_e32 v161, 0xbfb8aa3b, v157
	v_mul_f32_e32 v162, 0xbfb8aa3b, v158
	v_mul_f32_e32 v163, 0xbfb8aa3b, v159
	v_exp_f32_e32 v160, v160
	v_exp_f32_e32 v161, v161
	v_exp_f32_e32 v162, v162
	v_exp_f32_e32 v163, v163
	v_pk_mul_f32 v[24:25], v[24:25], v[140:141]
	v_pk_mul_f32 v[26:27], v[26:27], v[142:143]
	v_pk_add_f32 v[160:161], v[160:161], 1.0 op_sel_hi:[1,0]
	v_pk_add_f32 v[162:163], v[162:163], 1.0 op_sel_hi:[1,0]
	s_nop 0
	v_rcp_f32_e32 v160, v160
	v_rcp_f32_e32 v161, v161
	v_rcp_f32_e32 v162, v162
	v_rcp_f32_e32 v163, v163
	s_nop 0
	v_mul_f32_e32 v160, v156, v160
	v_mul_f32_e32 v161, v157, v161
	v_mul_f32_e32 v162, v158, v162
	v_mul_f32_e32 v163, v159, v163
	v_pk_mul_f32 v[24:25], v[24:25], v[160:161]
	v_pk_mul_f32 v[26:27], v[26:27], v[162:163]
	v_cvt_pk_bf16_f32 v176, v24, v25
	v_cvt_pk_bf16_f32 v177, v26, v27
	v_pk_mul_f32 v[24:25], v[16:17], v[0:1] op_sel_hi:[1,0]
	v_pk_mul_f32 v[26:27], v[14:15], v[0:1] op_sel_hi:[1,0]
	s_waitcnt vmcnt(4)
	v_lshlrev_b32_e32 v156, 16, v118
	v_and_b32_e32 v157, 0xffff0000, v118
	v_lshlrev_b32_e32 v158, 16, v119
	v_and_b32_e32 v159, 0xffff0000, v119
	v_mul_f32_e32 v160, 0xbfb8aa3b, v156
	v_mul_f32_e32 v161, 0xbfb8aa3b, v157
	v_mul_f32_e32 v162, 0xbfb8aa3b, v158
	v_mul_f32_e32 v163, 0xbfb8aa3b, v159
	v_exp_f32_e32 v160, v160
	v_exp_f32_e32 v161, v161
	v_exp_f32_e32 v162, v162
	v_exp_f32_e32 v163, v163
	v_pk_mul_f32 v[24:25], v[24:25], v[144:145]
	v_pk_mul_f32 v[26:27], v[26:27], v[146:147]
	v_pk_add_f32 v[160:161], v[160:161], 1.0 op_sel_hi:[1,0]
	v_pk_add_f32 v[162:163], v[162:163], 1.0 op_sel_hi:[1,0]
	s_nop 0
	v_rcp_f32_e32 v160, v160
	v_rcp_f32_e32 v161, v161
	v_rcp_f32_e32 v162, v162
	v_rcp_f32_e32 v163, v163
	s_nop 0
	v_mul_f32_e32 v160, v156, v160
	v_mul_f32_e32 v161, v157, v161
	v_mul_f32_e32 v162, v158, v162
	v_mul_f32_e32 v163, v159, v163
	v_pk_mul_f32 v[24:25], v[24:25], v[160:161]
	v_pk_mul_f32 v[26:27], v[26:27], v[162:163]
	v_cvt_pk_bf16_f32 v178, v24, v25
	v_cvt_pk_bf16_f32 v179, v26, v27
	s_nop 1
	v_permlane32_swap_b32_e32 v176, v178
	v_permlane32_swap_b32_e32 v177, v179
	global_store_dwordx4 v[184:185], v[176:179], off offset:64
	v_pk_mul_f32 v[24:25], v[12:13], v[0:1] op_sel_hi:[1,0]
	v_pk_mul_f32 v[26:27], v[4:5], v[0:1] op_sel_hi:[1,0]
	s_waitcnt vmcnt(4)
	v_lshlrev_b32_e32 v156, 16, v120
	v_and_b32_e32 v157, 0xffff0000, v120
	v_lshlrev_b32_e32 v158, 16, v121
	v_and_b32_e32 v159, 0xffff0000, v121
	v_mul_f32_e32 v160, 0xbfb8aa3b, v156
	v_mul_f32_e32 v161, 0xbfb8aa3b, v157
	v_mul_f32_e32 v162, 0xbfb8aa3b, v158
	v_mul_f32_e32 v163, 0xbfb8aa3b, v159
	v_exp_f32_e32 v160, v160
	v_exp_f32_e32 v161, v161
	v_exp_f32_e32 v162, v162
	v_exp_f32_e32 v163, v163
	v_pk_mul_f32 v[24:25], v[24:25], v[148:149]
	v_pk_mul_f32 v[26:27], v[26:27], v[150:151]
	v_pk_add_f32 v[160:161], v[160:161], 1.0 op_sel_hi:[1,0]
	v_pk_add_f32 v[162:163], v[162:163], 1.0 op_sel_hi:[1,0]
	s_nop 0
	v_rcp_f32_e32 v160, v160
	v_rcp_f32_e32 v161, v161
	v_rcp_f32_e32 v162, v162
	v_rcp_f32_e32 v163, v163
	s_nop 0
	v_mul_f32_e32 v160, v156, v160
	v_mul_f32_e32 v161, v157, v161
	v_mul_f32_e32 v162, v158, v162
	v_mul_f32_e32 v163, v159, v163
	v_pk_mul_f32 v[24:25], v[24:25], v[160:161]
	v_pk_mul_f32 v[26:27], v[26:27], v[162:163]
	v_cvt_pk_bf16_f32 v180, v24, v25
	v_cvt_pk_bf16_f32 v181, v26, v27
	v_pk_mul_f32 v[24:25], v[10:11], v[0:1] op_sel_hi:[1,0]
	v_pk_mul_f32 v[26:27], v[8:9], v[0:1] op_sel_hi:[1,0]
	s_waitcnt vmcnt(3)
	v_lshlrev_b32_e32 v156, 16, v122
	v_and_b32_e32 v157, 0xffff0000, v122
	v_lshlrev_b32_e32 v158, 16, v123
	v_and_b32_e32 v159, 0xffff0000, v123
	v_mul_f32_e32 v160, 0xbfb8aa3b, v156
	v_mul_f32_e32 v161, 0xbfb8aa3b, v157
	v_mul_f32_e32 v162, 0xbfb8aa3b, v158
	v_mul_f32_e32 v163, 0xbfb8aa3b, v159
	v_exp_f32_e32 v160, v160
	v_exp_f32_e32 v161, v161
	v_exp_f32_e32 v162, v162
	v_exp_f32_e32 v163, v163
	v_pk_mul_f32 v[24:25], v[24:25], v[152:153]
	v_pk_mul_f32 v[26:27], v[26:27], v[154:155]
	v_pk_add_f32 v[160:161], v[160:161], 1.0 op_sel_hi:[1,0]
	v_pk_add_f32 v[162:163], v[162:163], 1.0 op_sel_hi:[1,0]
	s_nop 0
	v_rcp_f32_e32 v160, v160
	v_rcp_f32_e32 v161, v161
	v_rcp_f32_e32 v162, v162
	v_rcp_f32_e32 v163, v163
	s_nop 0
	v_mul_f32_e32 v160, v156, v160
	v_mul_f32_e32 v161, v157, v161
	v_mul_f32_e32 v162, v158, v162
	v_mul_f32_e32 v163, v159, v163
	v_pk_mul_f32 v[24:25], v[24:25], v[160:161]
	v_pk_mul_f32 v[26:27], v[26:27], v[162:163]
	v_cvt_pk_bf16_f32 v182, v24, v25
	v_cvt_pk_bf16_f32 v183, v26, v27
	s_nop 1
	v_permlane32_swap_b32_e32 v180, v182
	v_permlane32_swap_b32_e32 v181, v183
	global_store_dwordx4 v[184:185], v[180:183], off offset:96
	s_branch .LBB0_216
